# v16 + unit-header tile-coordinate division by the row-group size (always 8 for 64 row tiles) replaced by shift/and
# baseline (speedup 1.0000x reference)
;     __host__ __device__ __forceinline__ bool next(int i, Unit& u) const {
;         const long L = (long)i * G + c; if (L >= nwg) return false;
;         int wgid = (int)L; { const int q = nwg / NXCD, r = nwg % NXCD, xcd = wgid % NXCD, off = wgid / NXCD; wgid = (xcd < r ? xcd * (q + 1) : r * (q + 1) + (xcd - r) * q) + off; }
;         const int nig = WGM * nN, gid = wgid / nig, fm = gid * WGM, gsz = (nM - fm) < WGM ? (nM - fm) : WGM;
;         u.pm = fm + ((wgid % nig) % gsz); u.pn = (wgid % nig) / gsz; u.seg = 0; return true;
.LBB0_535:
	s_add_i32 s8, s8, 1
	s_mul_i32 s6, s8, s12
	s_mul_hi_u32 s15, s8, s78
	s_add_i32 s15, s15, s6
	s_mul_i32 s6, s8, s78
	s_add_u32 s58, s6, s77
	s_addc_u32 s59, s15, s13
	v_cmp_gt_i64_e32 vcc, s[58:59], v[166:167]
	v_cmp_lt_i64_e64 s[42:43], s[58:59], v[164:165]
	s_cbranch_vccnz .LBB0_537
	s_ashr_i32 s6, s58, 31
	s_lshr_b32 s6, s6, 29
	s_add_i32 s6, s58, s6
	s_ashr_i32 s15, s6, 3
	s_and_b32 s6, s6, -8
	s_sub_i32 s6, s58, s6
	s_cmp_lt_i32 s6, 0
	s_movk_i32 s34, 0x161
	s_cselect_b32 s34, s34, 0x160
	s_mul_i32 s6, s6, s34
	s_add_i32 s6, s6, s15
	s_mul_hi_i32 s15, s6, 0x2e8ba2e9
	s_lshr_b32 s34, s15, 31
	s_ashr_i32 s15, s15, 6
	s_add_i32 s15, s15, s34
	s_lshl_b32 s34, s15, 3
	s_sub_i32 s35, 64, s34
	s_min_i32 s35, s35, 8
	s_mulk_i32 s15, 0x160
	s_sub_i32 s6, s6, s15
	s_abs_i32 s15, s6
	s_ashr_i32 s54, s6, 3
	s_and_b32 s6, s6, 7
	s_add_i32 s56, s34, s6

;     __host__ __device__ __forceinline__ bool next(int i, Unit& u) const {
;         const long L = (long)i * G + c; if (L >= nwg) return false;
;         int wgid = (int)L; { const int q = nwg / NXCD, r = nwg % NXCD, xcd = wgid % NXCD, off = wgid / NXCD; wgid = (xcd < r ? xcd * (q + 1) : r * (q + 1) + (xcd - r) * q) + off; }
;         const int nig = WGM * nN, gid = wgid / nig, fm = gid * WGM, gsz = (nM - fm) < WGM ? (nM - fm) : WGM;
;         u.pm = fm + ((wgid % nig) % gsz); u.pn = (wgid % nig) / gsz; u.seg = 0; return true;
.LBB0_605:
	s_add_i32 s56, s56, 1
	s_mul_i32 s31, s56, s45
	s_mul_hi_u32 s37, s56, s78
	s_add_i32 s37, s37, s31
	s_mul_i32 s31, s56, s78
	s_add_u32 s40, s31, s77
	s_addc_u32 s41, s37, s11
	v_cmp_gt_i64_e32 vcc, s[40:41], v[166:167]
	v_cmp_lt_i64_e64 s[38:39], s[40:41], v[164:165]
	s_cbranch_vccnz .LBB0_607
	s_ashr_i32 s30, s40, 31
	s_lshr_b32 s30, s30, 29
	s_add_i32 s30, s40, s30
	s_ashr_i32 s31, s30, 3
	s_and_b32 s30, s30, -8
	s_sub_i32 s30, s40, s30
	s_cmp_lt_i32 s30, 0
	s_movk_i32 s36, 0x161
	s_cselect_b32 s36, s36, 0x160
	s_mul_i32 s30, s30, s36
	s_add_i32 s30, s30, s31
	s_mul_hi_i32 s31, s30, 0x2e8ba2e9
	s_lshr_b32 s36, s31, 31
	s_ashr_i32 s31, s31, 6
	s_add_i32 s31, s31, s36
	s_lshl_b32 s36, s31, 3
	s_sub_i32 s37, 64, s36
	s_min_i32 s37, s37, 8
	s_mulk_i32 s31, 0x160
	s_sub_i32 s31, s30, s31
	s_abs_i32 s30, s31
	s_ashr_i32 s30, s31, 3
	s_and_b32 s31, s31, 7
	s_add_i32 s36, s36, s31

;     __host__ __device__ __forceinline__ bool next(int i, Unit& u) const {
;     ...
;         int wgid = (int)L; { const int q = nwg / NXCD, r = nwg % NXCD, xcd = wgid % NXCD, off = wgid / NXCD; wgid = (xcd < r ? xcd * (q + 1) : r * (q + 1) + (xcd - r) * q) + off; }
;         const int nig = WGM * nN, gid = wgid / nig, fm = gid * WGM, gsz = (nM - fm) < WGM ? (nM - fm) : WGM;
;         u.pm = fm + ((wgid % nig) % gsz); u.pn = (wgid % nig) / gsz; u.seg = 0; return true;
.LBB0_688:
	s_ashr_i32 s36, s38, 3
	s_add_i32 s36, s50, s36
	s_ashr_i32 s37, s36, 31
	s_lshr_b32 s37, s37, 26
	s_add_i32 s37, s36, s37
	s_ashr_i32 s38, s37, 6
	s_lshl_b32 s38, s38, 3
	s_sub_i32 s39, 64, s38
	s_min_i32 s39, s39, 8
	s_andn2_b32 s37, s37, 63
	s_sub_i32 s36, s36, s37
	s_abs_i32 s37, s36
	s_ashr_i32 s62, s36, 3
	s_and_b32 s36, s36, 7
	s_add_i32 s63, s38, s36

;     __host__ __device__ __forceinline__ bool next(int i, Unit& u) const {
;     ...
;         int wgid = (int)L; { const int q = nwg / NXCD, r = nwg % NXCD, xcd = wgid % NXCD, off = wgid / NXCD; wgid = (xcd < r ? xcd * (q + 1) : r * (q + 1) + (xcd - r) * q) + off; }
;         const int nig = WGM * nN, gid = wgid / nig, fm = gid * WGM, gsz = (nM - fm) < WGM ? (nM - fm) : WGM;
;         u.pm = fm + ((wgid % nig) % gsz); u.pn = (wgid % nig) / gsz; u.seg = 0; return true;
.LBB0_720:
	s_ashr_i32 s30, s36, 3
	s_add_i32 s30, s38, s30
	s_ashr_i32 s31, s30, 31
	s_lshr_b32 s31, s31, 26
	s_add_i32 s31, s30, s31
	s_ashr_i32 s36, s31, 6
	s_lshl_b32 s36, s36, 3
	s_sub_i32 s37, 64, s36
	s_min_i32 s37, s37, 8
	s_andn2_b32 s31, s31, 63
	s_sub_i32 s30, s30, s31
	s_abs_i32 s31, s30
	s_ashr_i32 s59, s30, 3
	s_and_b32 s30, s30, 7
	s_add_i32 s60, s36, s30

;     __host__ __device__ __forceinline__ bool next(int i, Unit& u) const {
;         const long L = (long)i * G + c; if (L >= nwg) return false;
;         int wgid = (int)L; { const int q = nwg / NXCD, r = nwg % NXCD, xcd = wgid % NXCD, off = wgid / NXCD; wgid = (xcd < r ? xcd * (q + 1) : r * (q + 1) + (xcd - r) * q) + off; }
;         const int nig = WGM * nN, gid = wgid / nig, fm = gid * WGM, gsz = (nM - fm) < WGM ? (nM - fm) : WGM;
;         u.pm = fm + ((wgid % nig) % gsz); u.pn = (wgid % nig) / gsz; u.seg = 0; return true;
.LBB0_920:
	s_add_i32 s75, s75, 1
	s_mul_i32 s6, s75, s67
	s_mul_hi_u32 s15, s75, s64
	s_add_i32 s15, s15, s6
	s_mul_i32 s6, s75, s64
	s_add_u32 s48, s6, s65
	s_addc_u32 s49, s15, s74
	v_cmp_gt_i64_e32 vcc, s[48:49], v[176:177]
	v_cmp_lt_i64_e64 s[38:39], s[48:49], v[174:175]
	s_cbranch_vccnz .LBB0_922
	s_ashr_i32 s6, s48, 31
	s_lshr_b32 s6, s6, 29
	s_add_i32 s6, s48, s6
	s_ashr_i32 s15, s6, 3
	s_and_b32 s6, s6, -8
	s_sub_i32 s6, s48, s6
	s_cmp_lt_i32 s6, 0
	s_movk_i32 s34, 0x121
	s_cselect_b32 s34, s34, 0x120
	s_mul_i32 s6, s6, s34
	s_add_i32 s6, s6, s15
	s_mul_hi_i32 s15, s6, 0x38e38e39
	s_lshr_b32 s34, s15, 31
	s_ashr_i32 s15, s15, 6
	s_add_i32 s15, s15, s34
	s_lshl_b32 s34, s15, 3
	s_sub_i32 s35, 64, s34
	s_min_i32 s35, s35, 8
	s_mulk_i32 s15, 0x120
	s_sub_i32 s6, s6, s15
	s_abs_i32 s15, s6
	s_ashr_i32 s36, s6, 3
	s_and_b32 s6, s6, 7
	s_add_i32 s46, s34, s6

;     __host__ __device__ __forceinline__ bool next(int i, Unit& u) const {
;         const long L = (long)i * G + c; if (L >= nwg) return false;
;         int wgid = (int)L; { const int q = nwg / NXCD, r = nwg % NXCD, xcd = wgid % NXCD, off = wgid / NXCD; wgid = (xcd < r ? xcd * (q + 1) : r * (q + 1) + (xcd - r) * q) + off; }
;         const int nig = WGM * nN, gid = wgid / nig, fm = gid * WGM, gsz = (nM - fm) < WGM ? (nM - fm) : WGM;
;         u.pm = fm + ((wgid % nig) % gsz); u.pn = (wgid % nig) / gsz; u.seg = 0; return true;
.LBB0_1130:
	s_add_i32 s66, s66, 1
	s_mul_i32 s31, s66, s59
	s_mul_hi_u32 s37, s66, s10
	s_add_i32 s37, s37, s31
	s_mul_i32 s31, s66, s10
	s_add_u32 s40, s31, s9
	s_addc_u32 s41, s37, s56
	v_cmp_gt_i64_e32 vcc, s[40:41], v[180:181]
	v_cmp_lt_i64_e64 s[38:39], s[40:41], v[178:179]
	s_cbranch_vccnz .LBB0_1132
	s_ashr_i32 s30, s40, 31
	s_lshr_b32 s30, s30, 29
	s_add_i32 s30, s40, s30
	s_ashr_i32 s31, s30, 3
	s_and_b32 s30, s30, -8
	s_sub_i32 s30, s40, s30
	s_cmp_lt_i32 s30, 0
	s_movk_i32 s36, 0xc1
	s_cselect_b32 s36, s36, 0xc0
	s_mul_i32 s30, s30, s36
	s_add_i32 s30, s30, s31
	s_mul_hi_i32 s31, s30, 0x2aaaaaab
	s_lshr_b32 s36, s31, 31
	s_ashr_i32 s31, s31, 5
	s_add_i32 s31, s31, s36
	s_lshl_b32 s36, s31, 3
	s_sub_i32 s37, 64, s36
	s_min_i32 s37, s37, 8
	s_mulk_i32 s31, 0xc0
	s_sub_i32 s31, s30, s31
	s_abs_i32 s30, s31
	s_ashr_i32 s30, s31, 3
	s_and_b32 s31, s31, 7
	s_add_i32 s36, s36, s31

;     __host__ __device__ __forceinline__ bool next(int i, Unit& u) const {
;         const long L = (long)i * G + c; if (L >= nwg) return false;
;         int wgid = (int)L; { const int q = nwg / NXCD, r = nwg % NXCD, xcd = wgid % NXCD, off = wgid / NXCD; wgid = (xcd < r ? xcd * (q + 1) : r * (q + 1) + (xcd - r) * q) + off; }
;         const int nig = WGM * nN, gid = wgid / nig, fm = gid * WGM, gsz = (nM - fm) < WGM ? (nM - fm) : WGM;
;         u.pm = fm + ((wgid % nig) % gsz); u.pn = (wgid % nig) / gsz; u.seg = 0; return true;
.LBB0_1150:
	s_add_i32 s76, s76, 1
	s_mul_i32 s6, s76, s74
	s_mul_hi_u32 s10, s76, s64
	s_add_i32 s10, s10, s6
	s_mul_i32 s6, s76, s64
	s_add_u32 s50, s6, s65
	s_addc_u32 s51, s10, s75
	v_cmp_gt_i64_e32 vcc, s[50:51], v[184:185]
	v_cmp_lt_i64_e64 s[38:39], s[50:51], v[182:183]
	s_cbranch_vccnz .LBB0_1152
	s_ashr_i32 s6, s50, 31
	s_lshr_b32 s6, s6, 29
	s_add_i32 s6, s50, s6
	s_ashr_i32 s10, s6, 3
	s_and_b32 s6, s6, -8
	s_sub_i32 s6, s50, s6
	s_cmp_lt_i32 s6, 0
	s_movk_i32 s11, 0x1e1
	s_cselect_b32 s11, s11, 0x1e0
	s_mul_i32 s6, s6, s11
	s_add_i32 s6, s6, s10
	s_mul_hi_i32 s10, s6, 0x88888889
	s_add_i32 s10, s10, s6
	s_lshr_b32 s11, s10, 31
	s_ashr_i32 s10, s10, 8
	s_add_i32 s10, s10, s11
	s_lshl_b32 s11, s10, 3
	s_sub_i32 s12, 64, s11
	s_min_i32 s12, s12, 8
	s_mulk_i32 s10, 0x1e0
	s_sub_i32 s6, s6, s10
	s_abs_i32 s10, s6
	s_ashr_i32 s18, s6, 3
	s_and_b32 s6, s6, 7
	s_add_i32 s48, s11, s6

;     __host__ __device__ __forceinline__ bool next(int i, Unit& u) const {
;     ...
;         int wgid = (int)L; { const int q = nwg / NXCD, r = nwg % NXCD, xcd = wgid % NXCD, off = wgid / NXCD; wgid = (xcd < r ? xcd * (q + 1) : r * (q + 1) + (xcd - r) * q) + off; }
;         const int nig = WGM * nN, gid = wgid / nig, fm = gid * WGM, gsz = (nM - fm) < WGM ? (nM - fm) : WGM;
;         u.pm = fm + ((wgid % nig) % gsz); u.pn = (wgid % nig) / gsz; u.seg = 0; return true;
.LBB0_2136:
	s_ashr_i32 s36, s40, 3
	s_add_i32 s36, s42, s36
	s_ashr_i32 s37, s36, 31
	s_lshr_b32 s37, s37, 26
	s_add_i32 s37, s36, s37
	s_ashr_i32 s40, s37, 6
	s_lshl_b32 s40, s40, 3
	s_sub_i32 s41, 64, s40
	s_min_i32 s41, s41, 8
	s_andn2_b32 s37, s37, 63
	s_sub_i32 s37, s36, s37
	s_abs_i32 s36, s37
	s_ashr_i32 s36, s37, 3
	s_and_b32 s37, s37, 7
	s_add_i32 s40, s40, s37
